# v18
# speedup vs baseline: 1.0098x; 1.0098x over previous
.LBB0_1372:
	s_add_i32 s40, s84, -2
	s_max_i32 s40, s40, 0
	s_lshl_b32 s12, s40, 13
	s_mov_b32 s13, 0
	s_lshl_b32 s24, s83, 13
	s_add_i32 m0, s74, s24
	v_lshl_add_u64 v[80:81], v[134:135], 0, s[12:13]
	global_load_lds_dwordx4 v[80:81], off
	s_lshl_b32 s12, s40, 14
	s_lshl_b32 s24, s83, 14
	s_add_i32 s24, s74, s24
	s_add_i32 m0, s24, 0x6000
	v_lshl_add_u64 v[80:81], v[132:133], 0, s[12:13]
	global_load_lds_dwordx4 v[80:81], off
	s_add_i32 m0, s24, 0x8000
	v_lshl_add_u64 v[80:81], v[80:81], 0, s[26:27]
	global_load_lds_dwordx4 v[80:81], off
	v_lshl_add_u32 v126, s81, 13, v153
	s_lshl_b32 s12, s81, 8
	v_add_u32_e32 v115, v126, v152
	v_add_u32_e32 v114, s12, v154
	ds_read_b128 v[208:211], v115 offset:4096
	ds_read_b128 v[80:83], v114 offset:128
	ds_read_b128 v[84:87], v114 offset:144
	ds_read_b128 v[88:91], v114 offset:192
	ds_read_b128 v[92:95], v114 offset:208
	ds_read_b128 v[224:227], v115
	ds_read_b128 v[192:195], v114
	ds_read_b128 v[196:199], v114 offset:16
	ds_read_b128 v[200:203], v114 offset:64
	ds_read_b128 v[204:207], v114 offset:80
	v_med3_i32 v118, v113, 0, v137
	v_lshlrev_b32_e32 v119, 2, v118
	global_load_dword v164, v119, s[54:55]
	v_add_u32_e32 v116, v126, v155
	v_add_u32_e32 v117, v126, v156
	v_add_u32_e32 v118, v126, v157
	s_waitcnt lgkmcnt(5)
	v_mfma_f32_32x32x16_bf16 v[80:95], v[208:211], v[108:111], v[80:95]
	ds_read_b128 v[212:215], v116 offset:4096
	ds_read_b128 v[228:231], v116
	s_waitcnt lgkmcnt(2)
	v_mfma_f32_32x32x16_bf16 v[192:207], v[224:227], v[108:111], v[192:207]
	ds_read_b128 v[216:219], v117 offset:4096
	ds_read_b128 v[232:235], v117
	s_waitcnt lgkmcnt(3)
	v_mfma_f32_32x32x16_bf16 v[80:95], v[212:215], v[104:107], v[80:95]
	s_waitcnt lgkmcnt(2)
	v_mfma_f32_32x32x16_bf16 v[192:207], v[228:231], v[104:107], v[192:207]
	ds_read_b128 v[220:223], v118 offset:4096
	ds_read_b128 v[236:239], v118
	s_waitcnt lgkmcnt(3)
	v_mfma_f32_32x32x16_bf16 v[80:95], v[216:219], v[100:103], v[80:95]
	s_waitcnt lgkmcnt(2)
	v_mfma_f32_32x32x16_bf16 v[192:207], v[232:235], v[100:103], v[192:207]
	s_waitcnt lgkmcnt(1)
	v_mfma_f32_32x32x16_bf16 v[80:95], v[220:223], v[96:99], v[80:95]
	s_waitcnt lgkmcnt(0)
	v_mfma_f32_32x32x16_bf16 v[192:207], v[236:239], v[96:99], v[192:207]
	s_and_b64 vcc, exec, s[8:9]
	s_cbranch_vccnz .LBB0_1375
	v_sub_u32_e32 v242, v148, v131
	v_cvt_f32_i32_e32 v242, v242
	v_lshl_add_u32 v243, s80, 8, v160
	v_mul_f32_e32 v242, v139, v242
	ds_write_b32 v243, v242
.LBB0_1375:
	s_add_i32 s24, s84, -1
	s_mov_b32 s12, s80
	s_nop 5
	v_max_f32_e32 v119, v81, v81
	v_max_f32_e32 v120, v80, v80
	v_max_f32_e32 v119, v120, v119
	v_max3_f32 v119, v119, v82, v83
	v_max_f32_e32 v240, v193, v193
	v_max_f32_e32 v241, v192, v192
	v_max3_f32 v119, v119, v84, v85
	v_max_f32_e32 v240, v241, v240
	v_max3_f32 v119, v119, v86, v87
	v_max3_f32 v240, v240, v194, v195
	v_max3_f32 v119, v119, v88, v89
	v_max3_f32 v240, v240, v196, v197
	v_max3_f32 v119, v119, v90, v91
	v_max3_f32 v240, v240, v198, v199
	v_max3_f32 v119, v119, v92, v93
	v_max3_f32 v240, v240, v200, v201
	v_max3_f32 v119, v119, v94, v95
	v_max3_f32 v240, v240, v202, v203
	v_max3_f32 v240, v240, v204, v205
	v_max3_f32 v240, v240, v206, v207
	v_cmp_lt_f32_e32 vcc, v119, v112
	s_cmp_eq_u64 vcc, exec
	s_cbranch_scc0 .LBB0_1377
	s_cmp_lt_i32 s84, 2
	s_waitcnt vmcnt(4) lgkmcnt(0)
	s_barrier
	v_subrev_u32_e32 v113, 64, v113
	s_mov_b64 s[42:43], 0
	s_mov_b64 s[40:41], s[10:11]
	s_waitcnt vmcnt(0)
	v_mov_b32_e32 v148, v164
	s_mov_b32 s80, s83
	s_mov_b32 s83, s81
	s_mov_b32 s84, 0
	s_cselect_b64 s[44:45], -1, 0
	s_mov_b32 s81, s12
	s_and_b64 vcc, exec, s[44:45]
	s_cbranch_vccz .LBB0_1378
	v_mov_b32_e32 v241, v240
	s_nop 1
	v_permlane32_swap_b32_e32 v240, v241
	v_max_f32_e32 v241, v241, v241
	v_max_f32_e32 v240, v240, v240
	v_max_f32_e32 v166, v240, v241
	v_mov_b64_e32 v[64:65], v[192:193]
	v_mov_b64_e32 v[66:67], v[194:195]
	v_mov_b64_e32 v[68:69], v[196:197]
	v_mov_b64_e32 v[70:71], v[198:199]
	v_mov_b64_e32 v[72:73], v[200:201]
	v_mov_b64_e32 v[74:75], v[202:203]
	v_mov_b64_e32 v[76:77], v[204:205]
	v_mov_b64_e32 v[78:79], v[206:207]
	s_branch .LBB0_1330
